# mixer queue: work-id atomic issued before the loop-top barrier, collected after it
# speedup vs baseline: 1.0081x; 1.0081x over previous
.LBB0_413:
	v_mov_b32_e32 v130, v220
	s_nop 0
	v_cmp_eq_u32_e32 vcc, 0, v130
	s_and_saveexec_b64 s[0:1], vcc
	s_cbranch_execz .Leq_nb
	v_mov_b32_e32 v2, 1
	global_atomic_add v2, v0, v2, s[48:49] sc0
.Leq_nb:
	s_or_b64 exec, exec, s[0:1]
	s_barrier
	s_and_saveexec_b64 s[0:1], vcc
	s_cbranch_execz .LBB0_417
	s_waitcnt vmcnt(0)
	v_mov_b32_e32 v1, s56
	ds_write_b32 v1, v2
